# P4 mem rms row stores widened dwordx2->dwordx4 via DPP lane-pair exchange
# speedup vs baseline: 1.0117x; 1.0092x over previous
; __device__ __forceinline__ void rms_row2048(const float* xrow, const float* g, bf16_t* orow, int lane) {
;     const f32x4* xr = (const f32x4*)xrow + lane; const f32x4* gr = (const f32x4*)g + lane;
;     f32x4 v[8]; float s = 0.f;
; #pragma unroll
;     for (int j = 0; j < 8; ++j) { v[j] = xr[64 * j]; s += (v[j].x * v[j].x + v[j].y * v[j].y) + (v[j].z * v[j].z + v[j].w * v[j].w); }
;     const float r = rsqrtf(wave_sum(s) * (1.f / 2048.f) + EPS);
; __global__ void __launch_bounds__(512, 2) mega_fwd(Args args) {
;     ...
;         for (int m = gw; m < NB * 256; m += NGW) rms_row2048(mem + (size_t)m * D, args.in[20], MEMN + (size_t)m * D, lane);
.LBB0_603:
	v_readlane_b32 s0, v238, 38
	s_cmpk_gt_i32 s0, 0x7ff
	v_readlane_b32 s1, v238, 39
	s_cbranch_scc1 .LBB0_606
	v_readlane_b32 s60, v238, 21
	v_lshlrev_b32_e32 v12, 4, v184
	v_mov_b32_e32 v13, 0
	v_readlane_b32 s68, v238, 29
	v_readlane_b32 s69, v238, 30
	s_mov_b64 s[0:1], 0x1000
	v_lshlrev_b32_e32 v10, 3, v184
	v_lshl_add_u64 v[0:1], s[68:69], 0, v[12:13]
	v_lshl_add_u64 v[2:3], v[0:1], 0, s[0:1]
	s_mov_b64 s[0:1], 0x1400
	v_lshl_add_u64 v[4:5], v[0:1], 0, s[0:1]
	s_mov_b64 s[0:1], 0x1800
	v_lshl_add_u64 v[6:7], v[0:1], 0, s[0:1]
	v_readlane_b32 s0, v238, 38
	v_readlane_b32 s1, v238, 39
	s_mov_b32 s10, s0
	s_ashr_i32 s11, s0, 31
	s_lshl_b64 s[0:1], s[10:11], 12
	s_add_u32 s0, s86, s0
	v_mov_b32_e32 v11, v13
	s_addc_u32 s1, s87, s1
	v_lshl_add_u64 v[10:11], s[0:1], 0, v[10:11]
	s_mov_b64 s[0:1], 0x1d800e00
	s_ashr_i32 s97, s96, 31
	v_lshl_add_u64 v[10:11], v[10:11], 0, s[0:1]
	s_lshl_b64 s[0:1], s[96:97], 12
	s_lshl_b64 s[6:7], s[10:11], 13
	s_add_u32 s6, s54, s6
	s_addc_u32 s7, s55, s7
	s_mov_b64 s[2:3], 0x1c00
	v_lshl_add_u64 v[12:13], s[6:7], 0, v[12:13]
	s_mov_b32 s8, s10
	v_readlane_b32 s61, v238, 22
	v_readlane_b32 s62, v238, 23
	v_readlane_b32 s63, v238, 24
	v_readlane_b32 s64, v238, 25
	v_readlane_b32 s65, v238, 26
	v_readlane_b32 s66, v238, 27
	v_readlane_b32 s67, v238, 28
	v_readlane_b32 s70, v238, 31
	v_readlane_b32 s71, v238, 32
	v_readlane_b32 s72, v238, 33
	v_readlane_b32 s73, v238, 34
	v_readlane_b32 s74, v238, 35
	v_readlane_b32 s75, v238, 36
	v_lshl_add_u64 v[8:9], v[0:1], 0, s[2:3]
	v_lshl_add_u64 v[12:13], v[12:13], 0, s[2:3]
	s_lshl_b64 s[2:3], s[96:97], 13
	v_mov_b32_e32 v14, 0x358637bd
	s_mov_b32 s6, 0x800000
	v_writelane_b32 v238, s8, 38
	s_mov_b32 s7, s10
	s_nop 0
	v_writelane_b32 v238, s9, 39
	v_and_b32_e32 v252, 1, v184
	v_lshrrev_b32_e32 v253, 1, v184
	v_lshlrev_b32_e32 v252, 9, v252
	v_lshl_add_u32 v252, v253, 4, v252
	v_lshlrev_b32_e32 v253, 3, v184
	v_sub_u32_e32 v252, v252, v253
	v_ashrrev_i32_e32 v253, 31, v252
	v_lshl_add_u64 v[10:11], v[10:11], 0, v[252:253]
	s_mov_b32 s32, 0xaaaaaaaa
	s_mov_b32 s33, 0xaaaaaaaa
.LBB0_605:
	v_add_co_u32_e32 v36, vcc, 0xfffff000, v12
	global_load_dwordx4 v[16:19], v[12:13], off offset:-3072
	global_load_dwordx4 v[20:23], v[12:13], off offset:-2048
	global_load_dwordx4 v[24:27], v[12:13], off offset:-1024
	v_addc_co_u32_e32 v37, vcc, -1, v13, vcc
	global_load_dwordx4 v[28:31], v[36:37], off offset:-3072
	global_load_dwordx4 v[32:35], v[36:37], off offset:-2048
	s_nop 0
	global_load_dwordx4 v[36:39], v[36:37], off offset:-1024
	s_nop 0
	global_load_dwordx4 v[40:43], v[12:13], off offset:-4096
	global_load_dwordx4 v[44:47], v[12:13], off
	global_load_dwordx4 v[48:51], v[0:1], off
	global_load_dwordx4 v[206:209], v[0:1], off offset:1024
	global_load_dwordx4 v[210:213], v[0:1], off offset:2048
	global_load_dwordx4 v[214:217], v[0:1], off offset:3072
	global_load_dwordx4 v[218:221], v[2:3], off
	global_load_dwordx4 v[222:225], v[4:5], off
	global_load_dwordx4 v[226:229], v[6:7], off
	global_load_dwordx4 v[230:233], v[8:9], off
	s_add_i32 s7, s7, s96
	s_cmpk_gt_i32 s7, 0x7ff
	v_lshl_add_u64 v[12:13], v[12:13], 0, s[2:3]
	s_waitcnt vmcnt(0)
	v_mov_b32_e32 v62, v29
	v_pk_mul_f32 v[52:53], v[22:23], v[22:23]
	v_pk_mul_f32 v[54:55], v[20:21], v[20:21]
	v_mul_f32_e32 v56, v25, v25
	v_mul_f32_e32 v58, v27, v27
	v_mul_f32_e32 v73, v46, v46
	v_mul_f32_e32 v80, v47, v47
	v_pk_mov_b32 v[60:61], v[54:55], v[52:53] op_sel:[1,0]
	v_mov_b32_e32 v55, v53
	v_pk_fma_f32 v[52:53], v[24:25], v[24:25], v[56:57] op_sel_hi:[1,1,0]
	v_pk_fma_f32 v[56:57], v[26:27], v[26:27], v[58:59] op_sel_hi:[1,1,0]
	v_mov_b32_e32 v63, v33
	v_mov_b32_e32 v66, v31
	v_mov_b32_e32 v67, v35
	v_mov_b32_e32 v58, v28
	v_mov_b32_e32 v59, v32
	v_mov_b32_e32 v64, v30
	v_mov_b32_e32 v65, v34
	v_pk_mul_f32 v[68:69], v[38:39], v[38:39]
	v_pk_mul_f32 v[70:71], v[36:37], v[36:37]
	v_pk_add_f32 v[54:55], v[60:61], v[54:55]
	v_mov_b32_e32 v53, v73
	v_mov_b32_e32 v57, v80
	v_pk_mul_f32 v[60:61], v[62:63], v[62:63]
	v_pk_mul_f32 v[62:63], v[66:67], v[66:67]
	v_pk_mov_b32 v[66:67], v[70:71], v[68:69] op_sel:[1,0]
	v_mov_b32_e32 v71, v69
	v_pk_add_f32 v[52:53], v[52:53], v[56:57]
	v_pk_fma_f32 v[56:57], v[58:59], v[58:59], v[60:61]
	v_pk_fma_f32 v[58:59], v[64:65], v[64:65], v[62:63]
	v_mul_f32_e32 v75, v17, v17
	v_mul_f32_e32 v72, v41, v41
	v_mul_f32_e32 v74, v43, v43
	v_pk_add_f32 v[60:61], v[66:67], v[70:71]
	v_pk_add_f32 v[56:57], v[56:57], v[58:59]
	v_mul_f32_e32 v15, v16, v16
	v_mul_f32_e32 v76, v18, v18
	v_mul_f32_e32 v77, v19, v19
	v_pk_fma_f32 v[68:69], v[40:41], v[40:41], v[72:73] op_sel_hi:[1,1,0]
	v_pk_fma_f32 v[72:73], v[42:43], v[42:43], v[74:75] op_sel_hi:[1,1,0]
	v_pk_add_f32 v[58:59], v[60:61], v[60:61] op_sel:[0,1] op_sel_hi:[1,0]
	v_pk_add_f32 v[56:57], v[56:57], v[56:57] op_sel:[0,1] op_sel_hi:[1,0]
	v_mov_b32_e32 v69, v76
	v_mov_b32_e32 v73, v77
	v_mov_b32_e32 v59, v75
	v_mov_b32_e32 v57, v15
	v_pk_add_f32 v[60:61], v[68:69], v[72:73]
	v_pk_add_f32 v[56:57], v[56:57], v[58:59]
	v_mul_f32_e32 v78, v44, v44
	v_pk_add_f32 v[56:57], v[56:57], v[60:61]
	v_mul_f32_e32 v79, v45, v45
	v_pk_add_f32 v[54:55], v[54:55], v[54:55] op_sel:[0,1] op_sel_hi:[1,0]
	v_pk_add_f32 v[56:57], v[56:57], v[56:57] op_sel:[0,1] op_sel_hi:[1,0]
	v_mov_b32_e32 v55, v79
	v_mov_b32_e32 v57, v78
	v_pk_add_f32 v[54:55], v[56:57], v[54:55]
	s_nop 0
	v_pk_add_f32 v[52:53], v[54:55], v[52:53]
	s_nop 0
	v_add_f32_e32 v15, v52, v53
	s_nop 1
	v_add_f32_dpp v15, v15, v15 quad_perm:[1,0,3,2] row_mask:0xf bank_mask:0xf bound_ctrl:1
	s_nop 1
	v_add_f32_dpp v15, v15, v15 quad_perm:[2,3,0,1] row_mask:0xf bank_mask:0xf bound_ctrl:1
	s_nop 1
; __device__ __forceinline__ unsigned pk2(float lo, float hi) { f32x2_t v = {lo, hi}; bf16x2_t b = __builtin_convertvector(v, bf16x2_t); return __builtin_bit_cast(unsigned, b); }
; __device__ __forceinline__ void rms_row2048(const float* xrow, const float* g, bf16_t* orow, int lane) {
;     ...
;     const float r = rsqrtf(wave_sum(s) * (1.f / 2048.f) + EPS);
;     u32x2* o8 = (u32x2*)orow + lane;
; #pragma unroll
;     for (int j = 0; j < 8; ++j) { const f32x4 gg = gr[64 * j]; u32x2 w; w.x = pk2(v[j].x * r * gg.x, v[j].y * r * gg.y); w.y = pk2(v[j].z * r * gg.z, v[j].w * r * gg.w); o8[64 * j] = w; }
	v_add_f32_dpp v15, v15, v15 row_half_mirror row_mask:0xf bank_mask:0xf bound_ctrl:1
	s_nop 1
	v_add_f32_dpp v15, v15, v15 row_mirror row_mask:0xf bank_mask:0xf bound_ctrl:1
	s_nop 0
	v_readlane_b32 s10, v15, 16
	v_readlane_b32 s11, v15, 48
	v_readlane_b32 s8, v15, 0
	v_readlane_b32 s9, v15, 32
	v_mov_b32_e32 v52, s10
	v_mov_b32_e32 v53, s11
	v_pk_add_f32 v[52:53], s[8:9], v[52:53]
	s_nop 0
	v_add_f32_e32 v15, v52, v53
	v_fmamk_f32 v15, v15, 0x3a000000, v14
	v_mul_f32_e32 v52, 0x4b800000, v15
	v_cmp_gt_f32_e32 vcc, s6, v15
	s_nop 1
	v_cndmask_b32_e32 v15, v15, v52, vcc
	v_rsq_f32_e32 v15, v15
	s_nop 0
	v_mul_f32_e32 v52, 0x45800000, v15
	v_cndmask_b32_e32 v52, v15, v52, vcc
	v_pk_mul_f32 v[28:29], v[28:29], v[52:53] op_sel_hi:[1,0]
	v_pk_mul_f32 v[30:31], v[30:31], v[52:53] op_sel_hi:[1,0]
	v_pk_mul_f32 v[28:29], v[48:49], v[28:29]
	v_pk_mul_f32 v[30:31], v[50:51], v[30:31]
	v_cvt_pk_bf16_f32 v244, v28, v29
	v_cvt_pk_bf16_f32 v245, v30, v31
	s_nop 0
	v_mov_b64_e32 v[28:29], v[206:207]
	v_mov_b64_e32 v[30:31], v[208:209]
	v_pk_mul_f32 v[32:33], v[32:33], v[52:53] op_sel_hi:[1,0]
	v_pk_mul_f32 v[34:35], v[34:35], v[52:53] op_sel_hi:[1,0]
	v_pk_mul_f32 v[16:17], v[16:17], v[52:53] op_sel_hi:[1,0]
	v_pk_mul_f32 v[18:19], v[18:19], v[52:53] op_sel_hi:[1,0]
	v_pk_mul_f32 v[20:21], v[20:21], v[52:53] op_sel_hi:[1,0]
	v_pk_mul_f32 v[22:23], v[22:23], v[52:53] op_sel_hi:[1,0]
	s_nop 0
	v_pk_mul_f32 v[28:29], v[28:29], v[32:33]
	v_pk_mul_f32 v[30:31], v[30:31], v[34:35]
	v_cvt_pk_bf16_f32 v246, v28, v29
	v_cvt_pk_bf16_f32 v247, v30, v31
	s_nop 1
	v_mov_b32_dpp v248, v244 quad_perm:[1,0,3,2] row_mask:0xf bank_mask:0xf
	v_mov_b32_dpp v249, v245 quad_perm:[1,0,3,2] row_mask:0xf bank_mask:0xf
	v_mov_b32_dpp v250, v246 quad_perm:[1,0,3,2] row_mask:0xf bank_mask:0xf
	v_mov_b32_dpp v251, v247 quad_perm:[1,0,3,2] row_mask:0xf bank_mask:0xf
	v_cndmask_b32_e64 v240, v244, v250, s[32:33]
	v_cndmask_b32_e64 v241, v245, v251, s[32:33]
	v_cndmask_b32_e64 v242, v248, v246, s[32:33]
	v_cndmask_b32_e64 v243, v249, v247, s[32:33]
	global_store_dwordx4 v[10:11], v[240:243], off offset:-3584
	v_mov_b64_e32 v[28:29], v[210:211]
	v_mov_b64_e32 v[30:31], v[212:213]
	v_pk_mul_f32 v[32:33], v[36:37], v[52:53] op_sel_hi:[1,0]
	v_pk_mul_f32 v[34:35], v[38:39], v[52:53] op_sel_hi:[1,0]
	s_nop 0
	v_pk_mul_f32 v[28:29], v[28:29], v[32:33]
	v_pk_mul_f32 v[30:31], v[30:31], v[34:35]
	v_cvt_pk_bf16_f32 v244, v28, v29
	v_cvt_pk_bf16_f32 v245, v30, v31
	s_nop 0
	v_mov_b64_e32 v[28:29], v[214:215]
	v_mov_b64_e32 v[30:31], v[216:217]
	v_pk_mul_f32 v[32:33], v[40:41], v[52:53] op_sel_hi:[1,0]
	v_pk_mul_f32 v[34:35], v[42:43], v[52:53] op_sel_hi:[1,0]
	s_nop 0
	v_pk_mul_f32 v[28:29], v[28:29], v[32:33]
	v_pk_mul_f32 v[30:31], v[30:31], v[34:35]
	v_cvt_pk_bf16_f32 v246, v28, v29
	v_cvt_pk_bf16_f32 v247, v30, v31
	s_nop 1
	v_mov_b32_dpp v248, v244 quad_perm:[1,0,3,2] row_mask:0xf bank_mask:0xf
	v_mov_b32_dpp v249, v245 quad_perm:[1,0,3,2] row_mask:0xf bank_mask:0xf
	v_mov_b32_dpp v250, v246 quad_perm:[1,0,3,2] row_mask:0xf bank_mask:0xf
	v_mov_b32_dpp v251, v247 quad_perm:[1,0,3,2] row_mask:0xf bank_mask:0xf
	v_cndmask_b32_e64 v240, v244, v250, s[32:33]
	v_cndmask_b32_e64 v241, v245, v251, s[32:33]
	v_cndmask_b32_e64 v242, v248, v246, s[32:33]
	v_cndmask_b32_e64 v243, v249, v247, s[32:33]
	global_store_dwordx4 v[10:11], v[240:243], off offset:-2560
	v_mov_b64_e32 v[28:29], v[218:219]
	v_mov_b64_e32 v[30:31], v[220:221]
	s_nop 0
	v_pk_mul_f32 v[16:17], v[28:29], v[16:17]
	v_pk_mul_f32 v[18:19], v[30:31], v[18:19]
	v_cvt_pk_bf16_f32 v244, v16, v17
	v_cvt_pk_bf16_f32 v245, v18, v19
	s_nop 0
	v_mov_b64_e32 v[16:17], v[222:223]
	v_mov_b64_e32 v[18:19], v[224:225]
	s_nop 0
	v_pk_mul_f32 v[16:17], v[20:21], v[16:17]
	v_pk_mul_f32 v[18:19], v[22:23], v[18:19]
	v_cvt_pk_bf16_f32 v246, v16, v17
	v_cvt_pk_bf16_f32 v247, v18, v19
	s_nop 1
	v_mov_b32_dpp v248, v244 quad_perm:[1,0,3,2] row_mask:0xf bank_mask:0xf
	v_mov_b32_dpp v249, v245 quad_perm:[1,0,3,2] row_mask:0xf bank_mask:0xf
	v_mov_b32_dpp v250, v246 quad_perm:[1,0,3,2] row_mask:0xf bank_mask:0xf
	v_mov_b32_dpp v251, v247 quad_perm:[1,0,3,2] row_mask:0xf bank_mask:0xf
	v_cndmask_b32_e64 v240, v244, v250, s[32:33]
	v_cndmask_b32_e64 v241, v245, v251, s[32:33]
	v_cndmask_b32_e64 v242, v248, v246, s[32:33]
	v_cndmask_b32_e64 v243, v249, v247, s[32:33]
	global_store_dwordx4 v[10:11], v[240:243], off offset:-1536
	v_mov_b64_e32 v[16:17], v[226:227]
	v_mov_b64_e32 v[18:19], v[228:229]
	v_pk_mul_f32 v[20:21], v[24:25], v[52:53] op_sel_hi:[1,0]
	v_pk_mul_f32 v[22:23], v[26:27], v[52:53] op_sel_hi:[1,0]
	s_nop 0
	v_pk_mul_f32 v[16:17], v[20:21], v[16:17]
	v_pk_mul_f32 v[18:19], v[22:23], v[18:19]
	v_cvt_pk_bf16_f32 v244, v16, v17
	v_cvt_pk_bf16_f32 v245, v18, v19
	s_nop 0
	v_mov_b64_e32 v[16:17], v[230:231]
	v_mov_b64_e32 v[18:19], v[232:233]
	v_pk_mul_f32 v[20:21], v[44:45], v[52:53] op_sel_hi:[1,0]
	v_pk_mul_f32 v[22:23], v[46:47], v[52:53] op_sel_hi:[1,0]
	s_nop 0
	v_pk_mul_f32 v[16:17], v[20:21], v[16:17]
	v_pk_mul_f32 v[18:19], v[22:23], v[18:19]
	v_cvt_pk_bf16_f32 v246, v16, v17
	v_cvt_pk_bf16_f32 v247, v18, v19
	s_nop 1
	v_mov_b32_dpp v248, v244 quad_perm:[1,0,3,2] row_mask:0xf bank_mask:0xf
	v_mov_b32_dpp v249, v245 quad_perm:[1,0,3,2] row_mask:0xf bank_mask:0xf
	v_mov_b32_dpp v250, v246 quad_perm:[1,0,3,2] row_mask:0xf bank_mask:0xf
	v_mov_b32_dpp v251, v247 quad_perm:[1,0,3,2] row_mask:0xf bank_mask:0xf
	v_cndmask_b32_e64 v240, v244, v250, s[32:33]
	v_cndmask_b32_e64 v241, v245, v251, s[32:33]
	v_cndmask_b32_e64 v242, v248, v246, s[32:33]
	v_cndmask_b32_e64 v243, v249, v247, s[32:33]
	global_store_dwordx4 v[10:11], v[240:243], off offset:-512
	v_lshl_add_u64 v[10:11], v[10:11], 0, s[0:1]
	s_cbranch_scc0 .LBB0_605
